# t4 + mixers weight-conversion loop: counted vmcnt(15..8) waits (dummy loads on tail paths) restore the 2-item software pipeline hipcc's join had drained with vmcnt(0)
# baseline (speedup 1.0000x reference)
; #define GAS __attribute__((address_space(1)))
; #define LAS __attribute__((address_space(3)))
; #define LDS_WAIT() asm volatile("s_waitcnt lgkmcnt(0)" ::: "memory")
; __device__ __forceinline__ unsigned pk2(float lo, float hi) { return pg8::cvt_pk_bf16(lo, hi); }
; __device__ __forceinline__ void conv_store(const ConvItem& c, int lane, const f32x4 (&v)[8], LAS float* scr) {
; #pragma unroll
;     for (int i = 0; i < 8; ++i) { LAS float* d = scr + (8 * i + (lane >> 3)) * 33 + 4 * (lane & 7); d[0] = v[i][0]; d[1] = v[i][1]; d[2] = v[i][2]; d[3] = v[i][3]; }
;     LDS_WAIT(); asm volatile("" ::: "memory");
;     const int cc = lane & 7;
; #pragma unroll
;     for (int j = 0; j < 4; ++j) { const int n = (lane >> 3) + 8 * j; const LAS float* s = scr + (8 * cc) * 33 + n;
;         v4u o; o.x = pk2(s[0 * 33], s[1 * 33]); o.y = pk2(s[2 * 33], s[3 * 33]); o.z = pk2(s[4 * 33], s[5 * 33]); o.w = pk2(s[6 * 33], s[7 * 33]);
;         *(GAS v4u*)(c.dst + (size_t)n * c.ldt + 8 * cc) = o; }
;     LDS_WAIT(); asm volatile("" ::: "memory");
.LBB0_651:
	s_waitcnt vmcnt(15)
	ds_write2_b32 v77, v38, v39 offset1:1
	ds_write2_b32 v77, v40, v41 offset0:2 offset1:3
	s_waitcnt vmcnt(14)
	ds_write2_b32 v79, v34, v35 offset1:1
	ds_write2_b32 v80, v36, v37 offset1:1
	s_waitcnt vmcnt(13)
	ds_write2_b32 v81, v46, v47 offset1:1
	ds_write2_b32 v82, v48, v49 offset1:1
	s_waitcnt vmcnt(12)
	ds_write2_b32 v83, v42, v43 offset1:1
	ds_write2_b32 v84, v44, v45 offset1:1
	s_waitcnt vmcnt(11)
	ds_write2_b32 v85, v54, v55 offset1:1
	ds_write2_b32 v86, v56, v57 offset1:1
	s_waitcnt vmcnt(10)
	ds_write2_b32 v87, v50, v51 offset1:1
	ds_write2_b32 v88, v52, v53 offset1:1
	s_waitcnt vmcnt(9)
	ds_write2_b32 v89, v62, v63 offset1:1
	ds_write2_b32 v90, v64, v65 offset1:1
	s_waitcnt vmcnt(8)
	ds_write2_b32 v91, v58, v59 offset1:1
	ds_write2_b32 v92, v60, v61 offset1:1
	s_waitcnt lgkmcnt(0)
	ds_read2_b32 v[86:87], v75 offset0:33 offset1:41
	ds_read2_b32 v[88:89], v75 offset1:8
	ds_read2_b32 v[90:91], v75 offset0:66 offset1:74
	ds_read2_b32 v[92:93], v75 offset0:99 offset1:107
	ds_read2_b32 v[94:95], v75 offset0:132 offset1:140
	ds_read2_b32 v[96:97], v75 offset0:165 offset1:173
	ds_read2_b32 v[98:99], v75 offset0:198 offset1:206
	ds_read2_b32 v[100:101], v75 offset0:231 offset1:239
	v_lshl_add_u64 v[84:85], s[8:9], 0, v[66:67]
	v_mad_u64_u32 v[102:103], s[8:9], s1, v68, 0
	s_waitcnt lgkmcnt(6)
	v_cvt_pk_bf16_f32 v80, v88, v86
	s_waitcnt lgkmcnt(4)
	v_cvt_pk_bf16_f32 v81, v90, v92
	s_waitcnt lgkmcnt(2)
	v_cvt_pk_bf16_f32 v82, v94, v96
	s_waitcnt lgkmcnt(0)
	v_cvt_pk_bf16_f32 v83, v98, v100
	v_lshl_add_u64 v[102:103], v[102:103], 1, v[84:85]
	global_store_dwordx4 v[102:103], v[80:83], off
	v_mad_u64_u32 v[102:103], s[8:9], s1, v74, 0
	s_nop 0
	v_cvt_pk_bf16_f32 v80, v89, v87
	v_mad_u64_u32 v[86:87], s[8:9], s1, v72, 0
	v_cvt_pk_bf16_f32 v81, v91, v93
	v_cvt_pk_bf16_f32 v82, v95, v97
	v_cvt_pk_bf16_f32 v83, v99, v101
	v_lshl_add_u64 v[86:87], v[86:87], 1, v[84:85]
	global_store_dwordx4 v[86:87], v[80:83], off
	ds_read2_b32 v[86:87], v75 offset0:16 offset1:24
	ds_read2_b32 v[88:89], v75 offset0:49 offset1:57
	ds_read2_b32 v[90:91], v75 offset0:82 offset1:90
	ds_read2_b32 v[92:93], v75 offset0:115 offset1:123
	ds_read2_b32 v[94:95], v75 offset0:148 offset1:156
	ds_read2_b32 v[96:97], v75 offset0:181 offset1:189
	ds_read2_b32 v[98:99], v75 offset0:214 offset1:222
	ds_read2_b32 v[100:101], v75 offset0:247 offset1:255
	v_lshl_add_u64 v[102:103], v[102:103], 1, v[84:85]
	s_waitcnt lgkmcnt(6)
	v_cvt_pk_bf16_f32 v80, v86, v88
	s_waitcnt lgkmcnt(4)
	v_cvt_pk_bf16_f32 v81, v90, v92
	s_waitcnt lgkmcnt(2)
	v_cvt_pk_bf16_f32 v82, v94, v96
	s_waitcnt lgkmcnt(0)
	v_cvt_pk_bf16_f32 v83, v98, v100
	global_store_dwordx4 v[102:103], v[80:83], off
	s_nop 1
	v_cvt_pk_bf16_f32 v80, v87, v89
	v_mad_u64_u32 v[86:87], s[8:9], s1, v76, 0
	v_cvt_pk_bf16_f32 v81, v91, v93
	v_cvt_pk_bf16_f32 v82, v95, v97
	v_cvt_pk_bf16_f32 v83, v99, v101
	v_lshl_add_u64 v[84:85], v[86:87], 1, v[84:85]
	global_store_dwordx4 v[84:85], v[80:83], off
	s_waitcnt lgkmcnt(0)

; #define GAS __attribute__((address_space(1)))
; #define LAS __attribute__((address_space(3)))
; #define LDS_WAIT() asm volatile("s_waitcnt lgkmcnt(0)" ::: "memory")
; __device__ __forceinline__ unsigned pk2(float lo, float hi) { return pg8::cvt_pk_bf16(lo, hi); }
; __device__ __forceinline__ void conv_store(const ConvItem& c, int lane, const f32x4 (&v)[8], LAS float* scr) {
; #pragma unroll
;     for (int i = 0; i < 8; ++i) { LAS float* d = scr + (8 * i + (lane >> 3)) * 33 + 4 * (lane & 7); d[0] = v[i][0]; d[1] = v[i][1]; d[2] = v[i][2]; d[3] = v[i][3]; }
;     LDS_WAIT(); asm volatile("" ::: "memory");
;     const int cc = lane & 7;
; #pragma unroll
;     for (int j = 0; j < 4; ++j) { const int n = (lane >> 3) + 8 * j; const LAS float* s = scr + (8 * cc) * 33 + n;
;         v4u o; o.x = pk2(s[0 * 33], s[1 * 33]); o.y = pk2(s[2 * 33], s[3 * 33]); o.z = pk2(s[4 * 33], s[5 * 33]); o.w = pk2(s[6 * 33], s[7 * 33]);
;         *(GAS v4u*)(c.dst + (size_t)n * c.ldt + 8 * cc) = o; }
;     LDS_WAIT(); asm volatile("" ::: "memory");
;     ...
;         const int itc = itb + ngw; const bool hc = itc < it_hi;
;         if (hc) { ca = conv_item(F, l, itc); conv_load(ca, F.lane, va); }
;         conv_store(cb, F.lane, vb, scr);
;         if (!hc) break;
;         it = itc;
.LBB0_670:
	v_add_u32_e32 v79, 0x420, v77
	v_add_u32_e32 v80, 0x428, v77
	v_add_u32_e32 v81, 0x840, v77
	v_add_u32_e32 v82, 0x848, v77
	v_add_u32_e32 v83, 0xc60, v77
	v_add_u32_e32 v84, 0xc68, v77
	v_add_u32_e32 v85, 0x1080, v77
	v_add_u32_e32 v86, 0x1088, v77
	v_add_u32_e32 v87, 0x14a0, v77
	v_add_u32_e32 v88, 0x14a8, v77
	v_add_u32_e32 v89, 0x18c0, v77
	v_add_u32_e32 v90, 0x18c8, v77
	v_add_u32_e32 v91, 0x1ce0, v77
	v_add_u32_e32 v92, 0x1ce8, v77
	s_waitcnt vmcnt(15)
	ds_write2_b32 v77, v2, v3 offset1:1
	ds_write2_b32 v77, v4, v5 offset0:2 offset1:3
	s_waitcnt vmcnt(14)
	ds_write2_b32 v79, v6, v7 offset1:1
	ds_write2_b32 v80, v8, v9 offset1:1
	s_waitcnt vmcnt(13)
	ds_write2_b32 v81, v10, v11 offset1:1
	ds_write2_b32 v82, v12, v13 offset1:1
	s_waitcnt vmcnt(12)
	ds_write2_b32 v83, v14, v15 offset1:1
	ds_write2_b32 v84, v16, v17 offset1:1
	s_waitcnt vmcnt(11)
	ds_write2_b32 v85, v18, v19 offset1:1
	ds_write2_b32 v86, v20, v21 offset1:1
	s_waitcnt vmcnt(10)
	ds_write2_b32 v87, v22, v23 offset1:1
	ds_write2_b32 v88, v24, v25 offset1:1
	s_waitcnt vmcnt(9)
	ds_write2_b32 v89, v26, v27 offset1:1
	ds_write2_b32 v90, v28, v29 offset1:1
	s_waitcnt vmcnt(8)
	ds_write2_b32 v91, v30, v31 offset1:1
	ds_write2_b32 v92, v32, v33 offset1:1
	s_waitcnt lgkmcnt(0)
	ds_read2_b32 v[100:101], v75 offset0:33 offset1:41
	ds_read2_b32 v[102:103], v75 offset1:8
	ds_read2_b32 v[104:105], v75 offset0:66 offset1:74
	ds_read2_b32 v[106:107], v75 offset0:99 offset1:107
	ds_read2_b32 v[108:109], v75 offset0:132 offset1:140
	ds_read2_b32 v[110:111], v75 offset0:165 offset1:173
	ds_read2_b32 v[112:113], v75 offset0:198 offset1:206
	ds_read2_b32 v[114:115], v75 offset0:231 offset1:239
	v_lshlrev_b32_e32 v66, 1, v78
	v_lshl_add_u64 v[98:99], s[6:7], 0, v[66:67]
	v_mad_u64_u32 v[116:117], s[2:3], s30, v68, 0
	s_waitcnt lgkmcnt(6)
	v_cvt_pk_bf16_f32 v94, v102, v100
	s_waitcnt lgkmcnt(4)
	v_cvt_pk_bf16_f32 v95, v104, v106
	s_waitcnt lgkmcnt(2)
	v_cvt_pk_bf16_f32 v96, v108, v110
	s_waitcnt lgkmcnt(0)
	v_cvt_pk_bf16_f32 v97, v112, v114
	v_lshl_add_u64 v[116:117], v[116:117], 1, v[98:99]
	global_store_dwordx4 v[116:117], v[94:97], off
	v_mad_u64_u32 v[116:117], s[2:3], s30, v74, 0
	s_nop 0
	v_cvt_pk_bf16_f32 v94, v103, v101
	v_mad_u64_u32 v[100:101], s[2:3], s30, v72, 0
	v_cvt_pk_bf16_f32 v95, v105, v107
	v_cvt_pk_bf16_f32 v96, v109, v111
	v_cvt_pk_bf16_f32 v97, v113, v115
	v_lshl_add_u64 v[100:101], v[100:101], 1, v[98:99]
	global_store_dwordx4 v[100:101], v[94:97], off
	ds_read2_b32 v[100:101], v75 offset0:16 offset1:24
	ds_read2_b32 v[102:103], v75 offset0:49 offset1:57
	ds_read2_b32 v[104:105], v75 offset0:82 offset1:90
	ds_read2_b32 v[106:107], v75 offset0:115 offset1:123
	ds_read2_b32 v[108:109], v75 offset0:148 offset1:156
	ds_read2_b32 v[110:111], v75 offset0:181 offset1:189
	ds_read2_b32 v[112:113], v75 offset0:214 offset1:222
	ds_read2_b32 v[114:115], v75 offset0:247 offset1:255
	v_lshl_add_u64 v[116:117], v[116:117], 1, v[98:99]
	s_waitcnt lgkmcnt(6)
	v_cvt_pk_bf16_f32 v94, v100, v102
	s_waitcnt lgkmcnt(4)
	v_cvt_pk_bf16_f32 v95, v104, v106
	s_waitcnt lgkmcnt(2)
	v_cvt_pk_bf16_f32 v96, v108, v110
	s_waitcnt lgkmcnt(0)
	v_cvt_pk_bf16_f32 v97, v112, v114
	global_store_dwordx4 v[116:117], v[94:97], off
	s_mov_b64 s[10:11], -1
	s_andn2_b64 vcc, exec, s[12:13]
	v_cvt_pk_bf16_f32 v94, v101, v103
	v_mad_u64_u32 v[100:101], s[2:3], s30, v76, 0
	v_cvt_pk_bf16_f32 v95, v105, v107
	v_cvt_pk_bf16_f32 v96, v109, v111
	v_cvt_pk_bf16_f32 v97, v113, v115
	v_lshl_add_u64 v[98:99], v[100:101], 1, v[98:99]
	global_store_dwordx4 v[98:99], v[94:97], off
	s_waitcnt lgkmcnt(0)
	s_cbranch_vccnz .LBB0_652
	s_add_i32 s2, s31, 16
	s_cmp_ge_i32 s2, s19
	s_cselect_b64 s[10:11], -1, 0
	s_and_b64 vcc, exec, s[10:11]
	s_cbranch_vccnz .LBB0_687
	s_cmpk_gt_i32 s31, 0x32ef
	s_mov_b64 s[16:17], -1
	s_cbranch_scc0 .LBB0_685
	s_cmpk_gt_u32 s2, 0x3aff
	s_cbranch_scc0 .LBB0_682
	s_cmpk_gt_u32 s2, 0x42ff
	s_cbranch_scc0 .LBB0_679
	s_cmpk_gt_u32 s2, 0x6eff
	s_mov_b64 s[14:15], -1
	s_cbranch_scc0 .LBB0_677
	s_load_dwordx2 s[6:7], s[64:65], 0xb8
	s_and_b32 s3, s2, 0x7fffffc0
	s_add_i32 s90, s3, 0xffff9100
	v_readlane_b32 s3, v255, 18
	s_waitcnt lgkmcnt(0)
	s_add_u32 s3, s6, s3
	v_readlane_b32 s6, v255, 17
	s_addc_u32 s12, s7, s6
	s_lshl_b64 s[6:7], s[90:91], 13
	s_add_u32 s3, s3, s6
	s_addc_u32 s6, s12, s7
	s_lshl_b32 s7, s2, 5
	s_and_b32 s7, s7, 0x7e0
	s_lshl_b32 s12, s7, 2
	s_add_u32 s12, s3, s12
	s_addc_u32 s13, s6, 0
	s_mulk_i32 s7, 0x2c00
	s_add_u32 s3, s22, s7
	s_addc_u32 s14, s23, 0
	s_lshl_b64 s[6:7], s[90:91], 1
	s_add_u32 s6, s3, s6
	s_addc_u32 s7, s14, s7
	s_mov_b64 s[14:15], 0

;     ...
;     for (;;) {
;         const int itb = it + ngw; const bool hb = itb < it_hi;
;         ConvItem cb = ca; f32x4 vb[8];
;         if (hb) { cb = conv_item(F, l, itb); conv_load(cb, F.lane, vb); }
;         conv_store(ca, F.lane, va, scr);
;         if (!hb) break;
;         const int itc = itb + ngw; const bool hc = itc < it_hi;
;         if (hc) { ca = conv_item(F, l, itc); conv_load(ca, F.lane, va); }
;         conv_store(cb, F.lane, vb, scr);
;         if (!hc) break;
;         it = itc;
;     }
.LBB0_687:
	global_load_dwordx4 v[2:5], v67, s[82:83]
	global_load_dwordx4 v[6:9], v67, s[82:83]
	global_load_dwordx4 v[10:13], v67, s[82:83]
	global_load_dwordx4 v[14:17], v67, s[82:83]
	global_load_dwordx4 v[18:21], v67, s[82:83]
	global_load_dwordx4 v[22:25], v67, s[82:83]
	global_load_dwordx4 v[26:29], v67, s[82:83]
	global_load_dwordx4 v[30:33], v67, s[82:83]
	s_mov_b32 s2, s31
	s_branch .LBB0_651
.Lcv_nohb:
	global_load_dwordx4 v[38:41], v67, s[82:83]
	global_load_dwordx4 v[34:37], v67, s[82:83]
	global_load_dwordx4 v[46:49], v67, s[82:83]
	global_load_dwordx4 v[42:45], v67, s[82:83]
	global_load_dwordx4 v[54:57], v67, s[82:83]
	global_load_dwordx4 v[50:53], v67, s[82:83]
	global_load_dwordx4 v[62:65], v67, s[82:83]
	global_load_dwordx4 v[58:61], v67, s[82:83]
	s_branch .LBB0_670

; __global__ void __launch_bounds__(NWAVES * 64, 2) mk_fwd(Args args) {
;     ...
;                 else if (q < e2) {
;                     const int j = q - e1; int ui = -1, ci = -1;
;                     if (j < 2 * nMin) { if (j & 1) ci = j >> 1; else ui = j >> 1; } else if (nU > nC) ui = nMin + (j - 2 * nMin); else ci = nMin + (j - 2 * nMin);
;                     if (ui >= 0) {
;                         pg8::Gemm g{(const pg8::bf16_t*)(F.ws + WS_H), (const pg8::bf16_t*)(wl + WL_IN), MT, INC, DM, DM}; pg8::DeferOrder S{ui};
;                         pg8::EpiIn E{(pg8::bf16_t*)(F.ws + WS_Z), (unsigned char*)(F.ws + WS_G), KIN(I_BGATE) + (size_t)l * GC, (const float*)(F.ws + WS_ROPE), (const float*)(F.ws + WS_ROPE) + 2048};
;                         pg8::gemm_phase<pg8::EpiIn, pg8::DeferOrder, true, true>(F.lds, g, S, E);
;                     } else convert_layer(F, l + 1, F.wave, NWAVES, ci * 256, ci * 256 + 256);
;                 }
.LBB0_693:
	s_waitcnt vmcnt(0)
	s_cbranch_execnz .LBB0_706
